# attention: in-wave software-pipelined loop (softmax of tile kt under the PV MFMAs of tile kt-1), no priority changes, with the item prologue/epilogue patches
# speedup vs baseline: 1.0070x; 1.0070x over previous
.LBB0_39:
	v_mov_b32_e32 v0, v220
	v_and_b32_e32 v4, 15, v0
	v_ashrrev_i32_e32 v1, 4, v0
	v_and_b32_e32 v6, 7, v0
	v_lshlrev_b32_e32 v10, 3, v4
	v_ashrrev_i32_e32 v5, 3, v0
	v_lshl_or_b32 v180, v1, 11, v10
	v_lshlrev_b32_e32 v10, 3, v6
	v_bfe_u32 v3, v0, 5, 1
	v_lshl_or_b32 v164, v5, 6, v10
	v_readlane_b32 s0, v251, 21
	v_readlane_b32 s1, v251, 22
	v_lshlrev_b64 v[0:1], 1, v[164:165]
	v_lshlrev_b32_e32 v164, 5, v3
	v_lshl_add_u64 v[190:191], s[0:1], 0, v[0:1]
	v_readlane_b32 s0, v251, 17
	v_readlane_b32 s1, v251, 18
	s_nop 1
	v_lshl_add_u64 v[192:193], s[0:1], 0, v[164:165]
	v_readlane_b32 s0, v251, 19
	v_readlane_b32 s1, v251, 20
	s_nop 1
	v_lshl_add_u64 v[194:195], s[0:1], 0, v[164:165]
	s_mov_b64 s[0:1], 0x39c6000
	v_lshl_add_u64 v[196:197], v[0:1], 0, s[0:1]
	v_add_u32_e32 v182, 0x10000, v180
	v_mov_b32_e32 v181, v165
	v_mov_b32_e32 v183, v165
	v_mov_b64_e32 v[0:1], 0xfe04000
	v_lshl_add_u64 v[198:199], v[180:181], 1, v[0:1]
	v_lshl_add_u64 v[200:201], v[182:183], 1, v[0:1]
	v_lshlrev_b32_e32 v2, 3, v3
	v_lshlrev_b32_e32 v164, 1, v2
	s_lshl_b32 s0, s28, 7
	s_and_b32 s70, s0, 0x380000
	s_lshl_b32 s0, s28, 12
	s_and_b32 s1, s24, 7
	s_and_b32 s0, s0, 0x7000000
	s_lshl_b32 s1, s1, 9
	v_lshl_add_u64 v[210:211], v[196:197], 0, s[70:71]
	s_or_b32 s70, s1, s0
	s_lshl_b32 s0, s5, 8
	s_add_i32 s43, s0, s25
	s_lshl_b32 s1, s29, 9
	v_or_b32_e32 v208, s43, v189
	v_lshl_add_u64 v[212:213], s[70:71], 0, v[198:199]
	v_lshl_add_u64 v[214:215], s[70:71], 0, v[200:201]
	v_lshl_add_u64 v[216:217], s[70:71], 0, v[202:203]
	v_lshl_add_u64 v[218:219], s[70:71], 0, v[204:205]
	s_and_b32 s70, s1, 0x7000
	v_ashrrev_i32_e32 v209, 31, v208
	v_lshl_add_u64 v[206:207], v[208:209], 0, s[70:71]
	v_mov_b64_e32 v[0:1], s[14:15]
	s_and_b32 s42, s29, 7
	v_mad_u64_u32 v[0:1], s[38:39], v206, s10, v[0:1]
	v_mad_i32_i24 v1, v207, s10, v1
	s_mul_i32 s38, s42, 0x180
	s_mov_b32 s39, s71
	v_lshl_add_u64 v[0:1], v[0:1], 0, s[38:39]
	v_lshlrev_b64 v[20:21], 7, v[206:207]
	v_lshl_add_u64 v[4:5], v[0:1], 0, v[164:165]
	v_lshl_add_u64 v[34:35], v[192:193], 0, v[20:21]
	v_lshl_add_u64 v[20:21], v[194:195], 0, v[20:21]
	global_load_dwordx4 v[132:135], v[4:5], off
	global_load_dwordx4 v[128:131], v[4:5], off offset:32
	global_load_dwordx4 v[124:127], v[4:5], off offset:64
	global_load_dwordx4 v[116:119], v[4:5], off offset:96
	global_load_dwordx4 v[112:115], v[4:5], off offset:128
	global_load_dwordx4 v[104:107], v[4:5], off offset:160
	global_load_dwordx4 v[100:103], v[4:5], off offset:192
	global_load_dwordx4 v[96:99], v[4:5], off offset:224
	global_load_dwordx4 v[8:11], v[4:5], off offset:256
	global_load_dwordx4 v[0:3], v[4:5], off offset:288
	global_load_dwordx4 v[12:15], v[4:5], off offset:320
	s_nop 0
	global_load_dwordx4 v[4:7], v[4:5], off offset:352
	s_nop 0
	global_load_dwordx4 v[16:19], v[34:35], off offset:16
	global_load_dwordx4 v[22:25], v[34:35], off
	global_load_dwordx4 v[26:29], v[20:21], off offset:16
	global_load_dwordx4 v[30:33], v[20:21], off
	global_load_dwordx4 v[64:67], v[34:35], off offset:80
	global_load_dwordx4 v[68:71], v[34:35], off offset:64
	global_load_dwordx4 v[72:75], v[20:21], off offset:80
	global_load_dwordx4 v[76:79], v[20:21], off offset:64
	s_lshl_b32 s1, s70, 12
	s_add_u32 s1, s96, s1
	s_addc_u32 s5, s97, 0
	s_lshl_b32 s7, s42, 9
	s_add_u32 s38, s1, s7
	s_addc_u32 s39, s5, 0
	s_lshl_b32 s70, s70, 7
	v_lshl_add_u64 v[148:149], v[180:181], 1, s[38:39]
	v_lshl_add_u64 v[150:151], v[182:183], 1, s[38:39]
	v_lshl_add_u64 v[152:153], v[190:191], 0, s[70:71]
	global_load_dwordx4 v[80:83], v[148:149], off
	global_load_dwordx4 v[84:87], v[150:151], off
	global_load_dwordx4 v[88:91], v[152:153], off
	global_load_dwordx4 v[92:95], v[148:149], off offset:256
	global_load_dwordx4 v[144:147], v[150:151], off offset:256
	s_or_b32 s44, s43, 31
	s_or_b32 s45, s0, 0xc0
	s_mov_b32 s46, 0
	v_mov_b32_e32 v209, 0
	v_mov_b32_e32 v247, 0xf149f2ca
	s_mov_b32 s13, 0
	s_waitcnt vmcnt(9)
	v_and_b32_e32 v37, 0xffff0000, v8
	v_lshlrev_b32_e32 v36, 16, v8
	s_waitcnt vmcnt(9)
	v_and_b32_e32 v39, 0xffff0000, v12
	v_lshlrev_b32_e32 v38, 16, v12
	v_lshlrev_b32_e32 v8, 16, v13
	s_waitcnt vmcnt(9)
	v_pk_mul_f32 v[40:41], v[30:31], v[36:37]
	v_pk_mul_f32 v[30:31], v[30:31], v[38:39]
	v_pk_fma_f32 v[40:41], v[22:23], v[38:39], v[40:41]
	v_pk_fma_f32 v[22:23], v[22:23], v[36:37], v[30:31] neg_lo:[0,0,1] neg_hi:[0,0,1]
	v_cvt_pk_bf16_f32 v108, v40, v41
	v_cvt_pk_bf16_f32 v120, v22, v23
	v_and_b32_e32 v23, 0xffff0000, v9
	v_lshlrev_b32_e32 v22, 16, v9
	v_and_b32_e32 v9, 0xffff0000, v13
	v_pk_mul_f32 v[12:13], v[32:33], v[22:23]
	s_nop 0
	v_pk_fma_f32 v[12:13], v[24:25], v[8:9], v[12:13]
	v_pk_mul_f32 v[8:9], v[32:33], v[8:9]
	v_cvt_pk_bf16_f32 v109, v12, v13
	v_pk_fma_f32 v[8:9], v[24:25], v[22:23], v[8:9] neg_lo:[0,0,1] neg_hi:[0,0,1]
	v_and_b32_e32 v13, 0xffff0000, v14
	v_cvt_pk_bf16_f32 v121, v8, v9
	v_and_b32_e32 v9, 0xffff0000, v10
	v_lshlrev_b32_e32 v8, 16, v10
	v_lshlrev_b32_e32 v12, 16, v14
	v_pk_mul_f32 v[22:23], v[26:27], v[8:9]
	v_lshlrev_b32_e32 v10, 16, v15
	v_pk_fma_f32 v[22:23], v[16:17], v[12:13], v[22:23]
	v_pk_mul_f32 v[12:13], v[26:27], v[12:13]
	v_cvt_pk_bf16_f32 v110, v22, v23
	v_pk_fma_f32 v[8:9], v[16:17], v[8:9], v[12:13] neg_lo:[0,0,1] neg_hi:[0,0,1]
	v_and_b32_e32 v25, 0xffff0000, v0
	v_cvt_pk_bf16_f32 v122, v8, v9
	v_and_b32_e32 v9, 0xffff0000, v11
	v_lshlrev_b32_e32 v8, 16, v11
	v_and_b32_e32 v11, 0xffff0000, v15
	v_pk_mul_f32 v[12:13], v[28:29], v[8:9]
	v_lshlrev_b32_e32 v24, 16, v0
	v_pk_fma_f32 v[12:13], v[18:19], v[10:11], v[12:13]
	v_pk_mul_f32 v[10:11], v[28:29], v[10:11]
	v_cvt_pk_bf16_f32 v111, v12, v13
	v_pk_fma_f32 v[8:9], v[18:19], v[8:9], v[10:11] neg_lo:[0,0,1] neg_hi:[0,0,1]
	v_and_b32_e32 v27, 0xffff0000, v4
	v_cvt_pk_bf16_f32 v123, v8, v9
	s_nop 0
	v_lshlrev_b32_e32 v26, 16, v4
	v_lshlrev_b32_e32 v0, 16, v5
	s_waitcnt vmcnt(5)
	v_mov_b32_e32 v8, v64
	v_mov_b32_e32 v9, v65
	v_mov_b32_e32 v10, v66
	v_mov_b32_e32 v11, v67
	v_mov_b32_e32 v16, v68
	v_mov_b32_e32 v17, v69
	v_mov_b32_e32 v18, v70
	v_mov_b32_e32 v19, v71
	v_mov_b32_e32 v12, v72
	v_mov_b32_e32 v13, v73
	v_mov_b32_e32 v14, v74
	v_mov_b32_e32 v15, v75
	v_mov_b32_e32 v20, v76
	v_mov_b32_e32 v21, v77
	v_mov_b32_e32 v22, v78
	v_mov_b32_e32 v23, v79
	v_pk_mul_f32 v[28:29], v[20:21], v[24:25]
	v_pk_mul_f32 v[20:21], v[20:21], v[26:27]
	v_pk_fma_f32 v[28:29], v[16:17], v[26:27], v[28:29]
	v_pk_fma_f32 v[16:17], v[16:17], v[24:25], v[20:21] neg_lo:[0,0,1] neg_hi:[0,0,1]
	v_cvt_pk_bf16_f32 v136, v28, v29
	v_cvt_pk_bf16_f32 v140, v16, v17
	v_and_b32_e32 v17, 0xffff0000, v1
	v_lshlrev_b32_e32 v16, 16, v1
	v_and_b32_e32 v1, 0xffff0000, v5
	v_pk_mul_f32 v[4:5], v[22:23], v[16:17]
	s_nop 0
	v_pk_fma_f32 v[4:5], v[18:19], v[0:1], v[4:5]
	v_pk_mul_f32 v[0:1], v[22:23], v[0:1]
	v_cvt_pk_bf16_f32 v137, v4, v5
	v_pk_fma_f32 v[0:1], v[18:19], v[16:17], v[0:1] neg_lo:[0,0,1] neg_hi:[0,0,1]
	v_and_b32_e32 v5, 0xffff0000, v6
	v_cvt_pk_bf16_f32 v141, v0, v1
	v_and_b32_e32 v1, 0xffff0000, v2
	v_lshlrev_b32_e32 v0, 16, v2
	v_lshlrev_b32_e32 v4, 16, v6
	v_pk_mul_f32 v[16:17], v[12:13], v[0:1]
	v_lshlrev_b32_e32 v2, 16, v7
	v_pk_fma_f32 v[16:17], v[8:9], v[4:5], v[16:17]
	v_pk_mul_f32 v[4:5], v[12:13], v[4:5]
	v_cvt_pk_bf16_f32 v138, v16, v17
	v_pk_fma_f32 v[0:1], v[8:9], v[0:1], v[4:5] neg_lo:[0,0,1] neg_hi:[0,0,1]
	v_cvt_pk_bf16_f32 v142, v0, v1
	v_and_b32_e32 v1, 0xffff0000, v3
	v_lshlrev_b32_e32 v0, 16, v3
	v_and_b32_e32 v3, 0xffff0000, v7
	v_pk_mul_f32 v[4:5], v[14:15], v[0:1]
	v_pk_fma_f32 v[4:5], v[10:11], v[2:3], v[4:5]
	v_pk_mul_f32 v[2:3], v[14:15], v[2:3]
	v_cvt_pk_bf16_f32 v139, v4, v5
	v_pk_fma_f32 v[0:1], v[10:11], v[0:1], v[2:3] neg_lo:[0,0,1] neg_hi:[0,0,1]
	s_nop 0
	v_cvt_pk_bf16_f32 v143, v0, v1
	s_waitcnt vmcnt(0)
	ds_write_b128 v244, v[80:83]
	s_waitcnt vmcnt(2)
	ds_write_b128 v244, v[84:87] offset:12800
	s_waitcnt vmcnt(1)
	ds_write_b128 v245, v[88:91] offset:256
	v_mov_b32_e32 v14, v165
	v_mov_b32_e32 v15, v165
	s_waitcnt vmcnt(0)
	s_movk_i32 s0, 320
	s_movk_i32 s1, 1280
	v_lshrrev_b32_e32 v216, 4, v220
	v_mul_u32_u24_e32 v216, s0, v216
	v_and_b32_e32 v248, 15, v220
	v_lshl_add_u32 v216, v248, 4, v216
	v_and_b32_e32 v217, 3, v220
	v_lshlrev_b32_e32 v217, 3, v217
	v_bfe_u32 v248, v220, 2, 2
	v_mad_u32_u24 v217, v248, s0, v217
	v_bfe_u32 v248, v220, 4, 1
	v_lshl_add_u32 v217, v248, 5, v217
	v_bfe_u32 v248, v220, 5, 1
	v_mad_u32_u24 v217, v248, s1, v217
	ds_write_b128 v216, v[92:95] offset:51200
	ds_write_b128 v216, v[144:147] offset:61440
	v_mov_b32_e32 v0, v165
	v_mov_b32_e32 v1, v165
	v_mov_b32_e32 v2, v165
	v_mov_b32_e32 v3, v165
	v_mov_b32_e32 v4, v165
	v_mov_b32_e32 v5, v165
	v_mov_b32_e32 v6, v165
	v_mov_b32_e32 v7, v165
	v_mov_b32_e32 v8, v165
	v_mov_b32_e32 v9, v165
	v_mov_b32_e32 v10, v165
	v_mov_b32_e32 v11, v165
	v_mov_b32_e32 v12, v165
	v_mov_b32_e32 v13, v165
	v_mov_b64_e32 v[30:31], v[14:15]
	v_mov_b64_e32 v[46:47], v[14:15]
	v_mov_b64_e32 v[62:63], v[14:15]
	v_mov_b64_e32 v[28:29], v[12:13]
	v_mov_b64_e32 v[26:27], v[10:11]
	v_mov_b64_e32 v[24:25], v[8:9]
	v_mov_b64_e32 v[22:23], v[6:7]
	v_mov_b64_e32 v[20:21], v[4:5]
	v_mov_b64_e32 v[18:19], v[2:3]
	v_mov_b64_e32 v[16:17], v[0:1]
	v_mov_b64_e32 v[44:45], v[12:13]
	v_mov_b64_e32 v[42:43], v[10:11]
	v_mov_b64_e32 v[40:41], v[8:9]
	v_mov_b64_e32 v[38:39], v[6:7]
	v_mov_b64_e32 v[36:37], v[4:5]
	v_mov_b64_e32 v[34:35], v[2:3]
	v_mov_b64_e32 v[32:33], v[0:1]
	v_mov_b64_e32 v[60:61], v[12:13]
	v_mov_b64_e32 v[58:59], v[10:11]
	v_mov_b64_e32 v[56:57], v[8:9]
	v_mov_b64_e32 v[54:55], v[6:7]
	v_mov_b64_e32 v[52:53], v[4:5]
	v_mov_b64_e32 v[50:51], v[2:3]
	v_mov_b64_e32 v[48:49], v[0:1]
	s_waitcnt lgkmcnt(0)
	s_barrier
	v_lshl_add_u64 v[248:249], s[20:21], 0, v[212:213]
	global_load_dwordx4 v[152:155], v[248:249], off
	v_lshl_add_u64 v[170:171], s[20:21], 0, v[214:215]
	global_load_dwordx4 v[156:159], v[170:171], off
	v_lshl_add_u64 v[218:219], s[20:21], 0, v[210:211]
	global_load_dwordx4 v[160:163], v[218:219], off
	global_load_dwordx4 v[144:147], v[248:249], off offset:256
	global_load_dwordx4 v[148:151], v[170:171], off offset:256
	s_mov_b64 s[38:39], 0x2000
	v_lshl_add_u64 v[210:211], v[210:211], 0, s[38:39]
	v_lshl_add_u64 v[212:213], v[212:213], 0, s[72:73]
	v_lshl_add_u64 v[214:215], v[214:215], 0, s[72:73]
